# same trims (no setprio, merged waits, M0 nops) applied to the two split-K tail GEMM loops; hipcc vmcnt(0) before three GEMM unit loops removed
# speedup vs baseline: 1.0041x; 1.0012x over previous
; #define PG8_STAGE(bufoff, gbase, voff) do { _Pragma("unroll") for (int _i = 0; _i < 2; ++_i) \
;         __builtin_amdgcn_global_load_lds((const unsigned*)((const char*)(gbase) + (voff)[_i]), (LAS unsigned*)(lds + (bufoff) + ldsw + _i * 8192), 16, 0, 0); } while (0)
; #define PG8_LDA(dst, b, h) do { _Pragma("unroll") for (int m = 0; m < 4; ++m) _Pragma("unroll") for (int k = 0; k < 2; ++k) dst[m][k] = *(const LAS bf16x8*)(lds + PG8_SA(b, h) + aoff + m * 2048 + k * 1024); } while (0)
; #define PG8_LDB(dst, b, h) do { _Pragma("unroll") for (int n = 0; n < 2; ++n) _Pragma("unroll") for (int k = 0; k < 2; ++k) dst[n][k] = *(const LAS bf16x8*)(lds + PG8_SB(b, h) + boff + n * 2048 + k * 1024); } while (0)
; #define PG8_WAIT_V(n) asm volatile("s_waitcnt vmcnt(" #n ")" ::: "memory")
; template <class Epi, class Sched = StaticOrder, bool ALIGN_EPI = true>
; __device__ __forceinline__ void gemm_phase(LAS unsigned char* lds, const Gemm g, const Sched& S, const Epi& E) {
;     ...
;         for (int t = 0; t < nt; t += 2) {
;             const bool last = (t == nt - 2);
;             const char* a1 = cA + (size_t)(t + 1) * kstep;
;             const char* a2 = last ? nA : cA + (size_t)(t + 2) * kstep; const char* b2 = last ? nB : cB + (size_t)(t + 2) * kstep;
;             const char* a3 = a2 + kstep; const char* b3 = b2 + kstep;
;             PG8_LDB(B0, 0, 0); PG8_LDB(B1, 0, 1); PG8_SCHED; PG8_LDA(At, 0, 0); PG8_STAGE(PG8_SA(1, 1), a1 + hstep, voffA);
;             PG8_WAIT_V(8); PG8_WAIT_L(0); PG8_BAR; PG8_MMA(0, 0, At, B0); PG8_MMA(0, 1, At, B1); PG8_BAR; PG8_SCHED;
;             PG8_LDA(At, 0, 1); PG8_STAGE(PG8_SB(0, 0), b2, voffB); PG8_STAGE(PG8_SB(0, 1), b2 + hstep, voffB); PG8_STAGE(PG8_SA(0, 0), a2, voffA);
;             PG8_WAIT_V(8); PG8_WAIT_L(0); PG8_BAR; PG8_MMA(1, 0, At, B0); PG8_MMA(1, 1, At, B1); PG8_BAR; PG8_SCHED;
;             PG8_LDB(B0, 1, 0); PG8_LDB(B1, 1, 1); PG8_SCHED; PG8_LDA(At, 1, 0); PG8_STAGE(PG8_SA(0, 1), a2 + hstep, voffA);
;             PG8_WAIT_V(8); PG8_WAIT_L(0); PG8_BAR; PG8_MMA(0, 0, At, B0); PG8_MMA(0, 1, At, B1); PG8_BAR; PG8_SCHED;
;             PG8_LDA(At, 1, 1); PG8_STAGE(PG8_SB(1, 0), b3, voffB); PG8_STAGE(PG8_SB(1, 1), b3 + hstep, voffB); PG8_STAGE(PG8_SA(1, 0), a3, voffA);
;             PG8_WAIT_V(8); PG8_WAIT_L(0); PG8_BAR; PG8_MMA(1, 0, At, B0); PG8_MMA(1, 1, At, B1); PG8_BAR; PG8_SCHED;
.LBB0_125:
	s_add_u32 vcc_lo, s80, 0x100
	s_addc_u32 vcc_hi, s81, 0
	s_add_i32 s16, 0, 0x10000
	s_cmp_eq_u32 s79, 4
	s_cselect_b32 s31, s47, vcc_hi
	s_cselect_b32 s30, s46, vcc_lo
	v_add_u32_e32 v141, s16, v1
	s_cselect_b32 s1, s13, s70
	s_cselect_b32 s0, s18, s41
	s_add_i32 s33, 0, 0x14000
	ds_read_b128 v[144:147], v141
	ds_read_b128 v[148:151], v141 offset:1024
	ds_read_b128 v[160:163], v141 offset:2048
	ds_read_b128 v[164:167], v141 offset:3072
	v_add_u32_e32 v141, s33, v1
	ds_read_b128 v[168:171], v141
	ds_read_b128 v[172:175], v141 offset:1024
	ds_read_b128 v[176:179], v141 offset:2048
	ds_read_b128 v[180:183], v141 offset:3072
	v_lshl_add_u64 v[152:153], s[80:81], 0, v[136:137]
	s_add_i32 m0, s6, 0xc000
	ds_read_b128 v[184:187], v142
	ds_read_b128 v[188:191], v142 offset:1024
	ds_read_b128 v[192:195], v142 offset:2048
	ds_read_b128 v[210:213], v142 offset:3072
	ds_read_b128 v[214:217], v142 offset:4096
	ds_read_b128 v[218:221], v142 offset:5120
	ds_read_b128 v[222:225], v142 offset:6144
	ds_read_b128 v[226:229], v142 offset:7168
	global_load_lds_dwordx4 v[152:153], off
	s_add_i32 m0, s6, 0xe000
	v_lshl_add_u64 v[152:153], s[80:81], 0, v[138:139]
	global_load_lds_dwordx4 v[152:153], off
	s_waitcnt vmcnt(8) lgkmcnt(0)
	s_barrier
	v_mfma_f32_16x16x32_bf16 v[126:129], v[144:147], v[184:187], v[126:129]
	v_mfma_f32_16x16x32_bf16 v[122:125], v[160:163], v[184:187], v[122:125]
	v_mfma_f32_16x16x32_bf16 v[118:121], v[144:147], v[192:195], v[118:121]
	v_mfma_f32_16x16x32_bf16 v[114:117], v[160:163], v[192:195], v[114:117]
	v_mfma_f32_16x16x32_bf16 v[110:113], v[144:147], v[214:217], v[110:113]
	v_mfma_f32_16x16x32_bf16 v[102:105], v[160:163], v[214:217], v[102:105]
	v_mfma_f32_16x16x32_bf16 v[94:97], v[144:147], v[222:225], v[94:97]
	v_mfma_f32_16x16x32_bf16 v[86:89], v[160:163], v[222:225], v[86:89]
	v_mfma_f32_16x16x32_bf16 v[126:129], v[148:151], v[188:191], v[126:129]
	v_mfma_f32_16x16x32_bf16 v[122:125], v[164:167], v[188:191], v[122:125]
	v_mfma_f32_16x16x32_bf16 v[118:121], v[148:151], v[210:213], v[118:121]
	v_mfma_f32_16x16x32_bf16 v[114:117], v[164:167], v[210:213], v[114:117]
	v_mfma_f32_16x16x32_bf16 v[110:113], v[148:151], v[218:221], v[110:113]
	v_mfma_f32_16x16x32_bf16 v[102:105], v[164:167], v[218:221], v[102:105]
	v_mfma_f32_16x16x32_bf16 v[94:97], v[148:151], v[226:229], v[94:97]
	v_mfma_f32_16x16x32_bf16 v[86:89], v[164:167], v[226:229], v[86:89]
	v_mfma_f32_16x16x32_bf16 v[106:109], v[168:171], v[184:187], v[106:109]
	v_mfma_f32_16x16x32_bf16 v[98:101], v[176:179], v[184:187], v[98:101]
	v_mfma_f32_16x16x32_bf16 v[90:93], v[168:171], v[192:195], v[90:93]
	v_mfma_f32_16x16x32_bf16 v[82:85], v[176:179], v[192:195], v[82:85]
	v_mfma_f32_16x16x32_bf16 v[78:81], v[168:171], v[214:217], v[78:81]
	v_mfma_f32_16x16x32_bf16 v[74:77], v[176:179], v[214:217], v[74:77]
	v_mfma_f32_16x16x32_bf16 v[70:73], v[168:171], v[222:225], v[70:73]
	v_mfma_f32_16x16x32_bf16 v[66:69], v[176:179], v[222:225], v[66:69]
	v_mfma_f32_16x16x32_bf16 v[106:109], v[172:175], v[188:191], v[106:109]
	v_mfma_f32_16x16x32_bf16 v[98:101], v[180:183], v[188:191], v[98:101]
	v_mfma_f32_16x16x32_bf16 v[90:93], v[172:175], v[210:213], v[90:93]
	v_mfma_f32_16x16x32_bf16 v[82:85], v[180:183], v[210:213], v[82:85]
	v_mfma_f32_16x16x32_bf16 v[78:81], v[172:175], v[218:221], v[78:81]
	v_mfma_f32_16x16x32_bf16 v[74:77], v[180:183], v[218:221], v[74:77]
	v_mfma_f32_16x16x32_bf16 v[70:73], v[172:175], v[226:229], v[70:73]
	v_mfma_f32_16x16x32_bf16 v[66:69], v[180:183], v[226:229], v[66:69]
	s_barrier
	s_add_i32 s16, s16, s5
	v_lshl_add_u64 v[152:153], s[0:1], 0, v[132:133]
	s_mov_b32 m0, s16
	ds_read_b128 v[184:187], v142 offset:16384
	ds_read_b128 v[188:191], v142 offset:17408
	ds_read_b128 v[192:195], v142 offset:18432
	ds_read_b128 v[210:213], v142 offset:19456
	ds_read_b128 v[214:217], v142 offset:20480
	ds_read_b128 v[218:221], v142 offset:21504
	ds_read_b128 v[222:225], v142 offset:22528
	ds_read_b128 v[226:229], v142 offset:23552
	global_load_lds_dwordx4 v[152:153], off
	s_add_i32 m0, s16, 0x2000
	s_add_u32 s16, s0, 0x80000
	v_lshl_add_u64 v[196:197], s[0:1], 0, v[130:131]
	s_addc_u32 s17, s1, 0
	s_add_i32 s33, s33, s5
	global_load_lds_dwordx4 v[196:197], off
	v_lshl_add_u64 v[230:231], s[16:17], 0, v[132:133]
	s_mov_b32 m0, s33
	v_lshl_add_u64 v[232:233], s[30:31], 0, v[130:131]
	global_load_lds_dwordx4 v[230:231], off
	s_add_i32 m0, s33, 0x2000
	v_lshl_add_u64 v[230:231], s[16:17], 0, v[130:131]
	global_load_lds_dwordx4 v[230:231], off
	s_mov_b32 m0, s6
	v_lshl_add_u64 v[230:231], s[30:31], 0, v[132:133]
	global_load_lds_dwordx4 v[230:231], off
	s_mov_b32 m0, s7
	s_nop 0
	global_load_lds_dwordx4 v[232:233], off
	s_waitcnt vmcnt(8) lgkmcnt(0)
	s_barrier
; #define PG8_STAGE(bufoff, gbase, voff) do { _Pragma("unroll") for (int _i = 0; _i < 2; ++_i) \
;         __builtin_amdgcn_global_load_lds((const unsigned*)((const char*)(gbase) + (voff)[_i]), (LAS unsigned*)(lds + (bufoff) + ldsw + _i * 8192), 16, 0, 0); } while (0)
; #define PG8_LDA(dst, b, h) do { _Pragma("unroll") for (int m = 0; m < 4; ++m) _Pragma("unroll") for (int k = 0; k < 2; ++k) dst[m][k] = *(const LAS bf16x8*)(lds + PG8_SA(b, h) + aoff + m * 2048 + k * 1024); } while (0)
; #define PG8_LDB(dst, b, h) do { _Pragma("unroll") for (int n = 0; n < 2; ++n) _Pragma("unroll") for (int k = 0; k < 2; ++k) dst[n][k] = *(const LAS bf16x8*)(lds + PG8_SB(b, h) + boff + n * 2048 + k * 1024); } while (0)
; #define PG8_MMA(ai, bj, At, Bt) do { __builtin_amdgcn_s_setprio(1); _Pragma("unroll") for (int m = 0; m < 4; ++m) _Pragma("unroll") for (int n = 0; n < 2; ++n) _Pragma("unroll") for (int k = 0; k < 2; ++k) \
;         acc[ai][bj][m][n] = __builtin_amdgcn_mfma_f32_16x16x32_bf16(Bt[n][k], At[m][k], acc[ai][bj][m][n], 0, 0, 0); __builtin_amdgcn_s_setprio(0); } while (0)
; #define PG8_WAIT_V(n) asm volatile("s_waitcnt vmcnt(" #n ")" ::: "memory")
; #define PG8_WAIT_L(n) asm volatile("s_waitcnt lgkmcnt(" #n ")" ::: "memory")
; #define PG8_BAR __builtin_amdgcn_s_barrier()
; #define PG8_SCHED __builtin_amdgcn_sched_barrier(0)
; template <class Epi, class Sched = StaticOrder, bool ALIGN_EPI = true>
; __device__ __forceinline__ void gemm_phase(LAS unsigned char* lds, const Gemm g, const Sched& S, const Epi& E) {
;     ...
;             PG8_WAIT_V(8); PG8_WAIT_L(0); PG8_BAR; PG8_MMA(1, 0, At, B0); PG8_MMA(1, 1, At, B1); PG8_BAR; PG8_SCHED;
;             PG8_LDB(B0, 1, 0); PG8_LDB(B1, 1, 1); PG8_SCHED; PG8_LDA(At, 1, 0); PG8_STAGE(PG8_SA(0, 1), a2 + hstep, voffA);
;             PG8_WAIT_V(8); PG8_WAIT_L(0); PG8_BAR; PG8_MMA(0, 0, At, B0); PG8_MMA(0, 1, At, B1); PG8_BAR; PG8_SCHED;
;             PG8_LDA(At, 1, 1); PG8_STAGE(PG8_SB(1, 0), b3, voffB); PG8_STAGE(PG8_SB(1, 1), b3 + hstep, voffB); PG8_STAGE(PG8_SA(1, 0), a3, voffA);
	v_mfma_f32_16x16x32_bf16 v[62:65], v[144:147], v[184:187], v[62:65]
	v_mfma_f32_16x16x32_bf16 v[58:61], v[160:163], v[184:187], v[58:61]
	v_mfma_f32_16x16x32_bf16 v[54:57], v[144:147], v[192:195], v[54:57]
	v_mfma_f32_16x16x32_bf16 v[50:53], v[160:163], v[192:195], v[50:53]
	v_mfma_f32_16x16x32_bf16 v[42:45], v[144:147], v[214:217], v[42:45]
	v_mfma_f32_16x16x32_bf16 v[34:37], v[160:163], v[214:217], v[34:37]
	v_mfma_f32_16x16x32_bf16 v[26:29], v[144:147], v[222:225], v[26:29]
	v_mfma_f32_16x16x32_bf16 v[18:21], v[160:163], v[222:225], v[18:21]
	v_mfma_f32_16x16x32_bf16 v[62:65], v[148:151], v[188:191], v[62:65]
	v_mfma_f32_16x16x32_bf16 v[58:61], v[164:167], v[188:191], v[58:61]
	v_mfma_f32_16x16x32_bf16 v[54:57], v[148:151], v[210:213], v[54:57]
	v_mfma_f32_16x16x32_bf16 v[50:53], v[164:167], v[210:213], v[50:53]
	v_mfma_f32_16x16x32_bf16 v[42:45], v[148:151], v[218:221], v[42:45]
	v_mfma_f32_16x16x32_bf16 v[34:37], v[164:167], v[218:221], v[34:37]
	v_mfma_f32_16x16x32_bf16 v[26:29], v[148:151], v[226:229], v[26:29]
	v_mfma_f32_16x16x32_bf16 v[18:21], v[164:167], v[226:229], v[18:21]
	v_mfma_f32_16x16x32_bf16 v[46:49], v[168:171], v[184:187], v[46:49]
	v_mfma_f32_16x16x32_bf16 v[38:41], v[176:179], v[184:187], v[38:41]
	v_mfma_f32_16x16x32_bf16 v[30:33], v[168:171], v[192:195], v[30:33]
	v_mfma_f32_16x16x32_bf16 v[22:25], v[176:179], v[192:195], v[22:25]
	v_mfma_f32_16x16x32_bf16 v[14:17], v[168:171], v[214:217], v[14:17]
	v_mfma_f32_16x16x32_bf16 v[10:13], v[176:179], v[214:217], v[10:13]
	v_mfma_f32_16x16x32_bf16 v[6:9], v[168:171], v[222:225], v[6:9]
	v_mfma_f32_16x16x32_bf16 v[2:5], v[176:179], v[222:225], v[2:5]
	v_mfma_f32_16x16x32_bf16 v[46:49], v[172:175], v[188:191], v[46:49]
	v_mfma_f32_16x16x32_bf16 v[38:41], v[180:183], v[188:191], v[38:41]
	v_mfma_f32_16x16x32_bf16 v[30:33], v[172:175], v[210:213], v[30:33]
	v_mfma_f32_16x16x32_bf16 v[22:25], v[180:183], v[210:213], v[22:25]
	v_mfma_f32_16x16x32_bf16 v[14:17], v[172:175], v[218:221], v[14:17]
	v_mfma_f32_16x16x32_bf16 v[10:13], v[180:183], v[218:221], v[10:13]
	v_mfma_f32_16x16x32_bf16 v[6:9], v[172:175], v[226:229], v[6:9]
	v_mfma_f32_16x16x32_bf16 v[2:5], v[180:183], v[226:229], v[2:5]
	s_barrier
	s_add_i32 s33, 0, 0x18000
	v_add_u32_e32 v141, s33, v1
	s_add_i32 s80, 0, 0x1c000
	ds_read_b128 v[144:147], v141
	ds_read_b128 v[148:151], v141 offset:1024
	ds_read_b128 v[160:163], v141 offset:2048
	ds_read_b128 v[164:167], v141 offset:3072
	v_add_u32_e32 v141, s80, v1
	ds_read_b128 v[168:171], v141
	ds_read_b128 v[172:175], v141 offset:1024
	ds_read_b128 v[176:179], v141 offset:2048
	ds_read_b128 v[180:183], v141 offset:3072
	s_add_u32 s16, s30, 0x80000
	s_addc_u32 s17, s31, 0
	s_mov_b32 m0, s8
	v_lshl_add_u64 v[234:235], s[16:17], 0, v[132:133]
	ds_read_b128 v[184:187], v142 offset:32768
	ds_read_b128 v[188:191], v142 offset:33792
	ds_read_b128 v[192:195], v142 offset:34816
	ds_read_b128 v[210:213], v142 offset:35840
	ds_read_b128 v[214:217], v142 offset:36864
	ds_read_b128 v[218:221], v142 offset:37888
	ds_read_b128 v[222:225], v142 offset:38912
	ds_read_b128 v[226:229], v142 offset:39936
	global_load_lds_dwordx4 v[234:235], off
	s_mov_b32 m0, s9
	v_lshl_add_u64 v[234:235], s[16:17], 0, v[130:131]
	global_load_lds_dwordx4 v[234:235], off
	s_waitcnt vmcnt(8) lgkmcnt(0)
	s_barrier
	v_mfma_f32_16x16x32_bf16 v[126:129], v[144:147], v[184:187], v[126:129]
	v_mfma_f32_16x16x32_bf16 v[122:125], v[160:163], v[184:187], v[122:125]
	v_mfma_f32_16x16x32_bf16 v[118:121], v[144:147], v[192:195], v[118:121]
	v_mfma_f32_16x16x32_bf16 v[114:117], v[160:163], v[192:195], v[114:117]
	v_mfma_f32_16x16x32_bf16 v[110:113], v[144:147], v[214:217], v[110:113]
	v_mfma_f32_16x16x32_bf16 v[102:105], v[160:163], v[214:217], v[102:105]
	v_mfma_f32_16x16x32_bf16 v[94:97], v[144:147], v[222:225], v[94:97]
	v_mfma_f32_16x16x32_bf16 v[86:89], v[160:163], v[222:225], v[86:89]
	v_mfma_f32_16x16x32_bf16 v[126:129], v[148:151], v[188:191], v[126:129]
	v_mfma_f32_16x16x32_bf16 v[122:125], v[164:167], v[188:191], v[122:125]
	v_mfma_f32_16x16x32_bf16 v[118:121], v[148:151], v[210:213], v[118:121]
	v_mfma_f32_16x16x32_bf16 v[114:117], v[164:167], v[210:213], v[114:117]
	v_mfma_f32_16x16x32_bf16 v[110:113], v[148:151], v[218:221], v[110:113]
	v_mfma_f32_16x16x32_bf16 v[102:105], v[164:167], v[218:221], v[102:105]
	v_mfma_f32_16x16x32_bf16 v[94:97], v[148:151], v[226:229], v[94:97]
	v_mfma_f32_16x16x32_bf16 v[86:89], v[164:167], v[226:229], v[86:89]
	v_mfma_f32_16x16x32_bf16 v[106:109], v[168:171], v[184:187], v[106:109]
	v_mfma_f32_16x16x32_bf16 v[98:101], v[176:179], v[184:187], v[98:101]
	v_mfma_f32_16x16x32_bf16 v[90:93], v[168:171], v[192:195], v[90:93]
	v_mfma_f32_16x16x32_bf16 v[82:85], v[176:179], v[192:195], v[82:85]
	v_mfma_f32_16x16x32_bf16 v[78:81], v[168:171], v[214:217], v[78:81]
	v_mfma_f32_16x16x32_bf16 v[74:77], v[176:179], v[214:217], v[74:77]
	v_mfma_f32_16x16x32_bf16 v[70:73], v[168:171], v[222:225], v[70:73]
	v_mfma_f32_16x16x32_bf16 v[66:69], v[176:179], v[222:225], v[66:69]
	v_mfma_f32_16x16x32_bf16 v[106:109], v[172:175], v[188:191], v[106:109]
	v_mfma_f32_16x16x32_bf16 v[98:101], v[180:183], v[188:191], v[98:101]
	v_mfma_f32_16x16x32_bf16 v[90:93], v[172:175], v[210:213], v[90:93]
	v_mfma_f32_16x16x32_bf16 v[82:85], v[180:183], v[210:213], v[82:85]
	v_mfma_f32_16x16x32_bf16 v[78:81], v[172:175], v[218:221], v[78:81]
	v_mfma_f32_16x16x32_bf16 v[74:77], v[180:183], v[218:221], v[74:77]
	v_mfma_f32_16x16x32_bf16 v[70:73], v[172:175], v[226:229], v[70:73]
	v_mfma_f32_16x16x32_bf16 v[66:69], v[180:183], v[226:229], v[66:69]
	s_barrier
; #define PG8_STAGE(bufoff, gbase, voff) do { _Pragma("unroll") for (int _i = 0; _i < 2; ++_i) \
;         __builtin_amdgcn_global_load_lds((const unsigned*)((const char*)(gbase) + (voff)[_i]), (LAS unsigned*)(lds + (bufoff) + ldsw + _i * 8192), 16, 0, 0); } while (0)
; #define PG8_LDA(dst, b, h) do { _Pragma("unroll") for (int m = 0; m < 4; ++m) _Pragma("unroll") for (int k = 0; k < 2; ++k) dst[m][k] = *(const LAS bf16x8*)(lds + PG8_SA(b, h) + aoff + m * 2048 + k * 1024); } while (0)
; #define PG8_MMA(ai, bj, At, Bt) do { __builtin_amdgcn_s_setprio(1); _Pragma("unroll") for (int m = 0; m < 4; ++m) _Pragma("unroll") for (int n = 0; n < 2; ++n) _Pragma("unroll") for (int k = 0; k < 2; ++k) \
;         acc[ai][bj][m][n] = __builtin_amdgcn_mfma_f32_16x16x32_bf16(Bt[n][k], At[m][k], acc[ai][bj][m][n], 0, 0, 0); __builtin_amdgcn_s_setprio(0); } while (0)
; #define PG8_WAIT_V(n) asm volatile("s_waitcnt vmcnt(" #n ")" ::: "memory")
; #define PG8_WAIT_L(n) asm volatile("s_waitcnt lgkmcnt(" #n ")" ::: "memory")
; #define PG8_BAR __builtin_amdgcn_s_barrier()
; #define PG8_SCHED __builtin_amdgcn_sched_barrier(0)
; template <class Epi, class Sched = StaticOrder, bool ALIGN_EPI = true>
; __device__ __forceinline__ void gemm_phase(LAS unsigned char* lds, const Gemm g, const Sched& S, const Epi& E) {
;     ...
;             PG8_LDA(At, 1, 1); PG8_STAGE(PG8_SB(1, 0), b3, voffB); PG8_STAGE(PG8_SB(1, 1), b3 + hstep, voffB); PG8_STAGE(PG8_SA(1, 0), a3, voffA);
;             PG8_WAIT_V(8); PG8_WAIT_L(0); PG8_BAR; PG8_MMA(1, 0, At, B0); PG8_MMA(1, 1, At, B1); PG8_BAR; PG8_SCHED;
;         }
;         if constexpr (ALIGN_EPI) { if (wr == 0) PG8_BAR; }
	s_add_i32 s16, s33, s5
	v_lshl_add_u64 v[152:153], v[152:153], 0, s[34:35]
	s_mov_b32 m0, s16
	ds_read_b128 v[184:187], v142 offset:49152
	ds_read_b128 v[188:191], v142 offset:50176
	ds_read_b128 v[192:195], v142 offset:51200
	ds_read_b128 v[210:213], v142 offset:52224
	ds_read_b128 v[214:217], v142 offset:53248
	ds_read_b128 v[218:221], v142 offset:54272
	ds_read_b128 v[222:225], v142 offset:55296
	ds_read_b128 v[226:229], v142 offset:56320
	global_load_lds_dwordx4 v[152:153], off
	s_add_i32 m0, s16, 0x2000
	s_add_u32 s0, s0, 0x80080
	v_lshl_add_u64 v[152:153], v[196:197], 0, s[34:35]
	s_addc_u32 s1, s1, 0
	s_add_i32 s16, s80, s5
	global_load_lds_dwordx4 v[152:153], off
	s_mov_b32 m0, s16
	v_lshl_add_u64 v[152:153], s[0:1], 0, v[132:133]
	global_load_lds_dwordx4 v[152:153], off
	s_add_i32 m0, s16, 0x2000
	v_lshl_add_u64 v[152:153], s[0:1], 0, v[130:131]
	global_load_lds_dwordx4 v[152:153], off
	s_mov_b32 m0, s22
	v_lshl_add_u64 v[152:153], v[230:231], 0, s[34:35]
	global_load_lds_dwordx4 v[152:153], off
	s_mov_b32 m0, s23
	v_lshl_add_u64 v[152:153], v[232:233], 0, s[34:35]
	global_load_lds_dwordx4 v[152:153], off
	s_waitcnt vmcnt(8) lgkmcnt(0)
	s_barrier
	v_mfma_f32_16x16x32_bf16 v[62:65], v[144:147], v[184:187], v[62:65]
	v_mfma_f32_16x16x32_bf16 v[58:61], v[160:163], v[184:187], v[58:61]
	v_mfma_f32_16x16x32_bf16 v[54:57], v[144:147], v[192:195], v[54:57]
	v_mfma_f32_16x16x32_bf16 v[50:53], v[160:163], v[192:195], v[50:53]
	v_mfma_f32_16x16x32_bf16 v[42:45], v[144:147], v[214:217], v[42:45]
	v_mfma_f32_16x16x32_bf16 v[34:37], v[160:163], v[214:217], v[34:37]
	v_mfma_f32_16x16x32_bf16 v[26:29], v[144:147], v[222:225], v[26:29]
	v_mfma_f32_16x16x32_bf16 v[18:21], v[160:163], v[222:225], v[18:21]
	v_mfma_f32_16x16x32_bf16 v[62:65], v[148:151], v[188:191], v[62:65]
	v_mfma_f32_16x16x32_bf16 v[58:61], v[164:167], v[188:191], v[58:61]
	v_mfma_f32_16x16x32_bf16 v[54:57], v[148:151], v[210:213], v[54:57]
	v_mfma_f32_16x16x32_bf16 v[50:53], v[164:167], v[210:213], v[50:53]
	v_mfma_f32_16x16x32_bf16 v[42:45], v[148:151], v[218:221], v[42:45]
	v_mfma_f32_16x16x32_bf16 v[34:37], v[164:167], v[218:221], v[34:37]
	v_mfma_f32_16x16x32_bf16 v[26:29], v[148:151], v[226:229], v[26:29]
	v_mfma_f32_16x16x32_bf16 v[18:21], v[164:167], v[226:229], v[18:21]
	v_mfma_f32_16x16x32_bf16 v[46:49], v[168:171], v[184:187], v[46:49]
	v_mfma_f32_16x16x32_bf16 v[38:41], v[176:179], v[184:187], v[38:41]
	v_mfma_f32_16x16x32_bf16 v[30:33], v[168:171], v[192:195], v[30:33]
	v_mfma_f32_16x16x32_bf16 v[22:25], v[176:179], v[192:195], v[22:25]
	v_mfma_f32_16x16x32_bf16 v[14:17], v[168:171], v[214:217], v[14:17]
	v_mfma_f32_16x16x32_bf16 v[10:13], v[176:179], v[214:217], v[10:13]
	v_mfma_f32_16x16x32_bf16 v[6:9], v[168:171], v[222:225], v[6:9]
	v_mfma_f32_16x16x32_bf16 v[2:5], v[176:179], v[222:225], v[2:5]
	v_mfma_f32_16x16x32_bf16 v[46:49], v[172:175], v[188:191], v[46:49]
	v_mfma_f32_16x16x32_bf16 v[38:41], v[180:183], v[188:191], v[38:41]
	v_mfma_f32_16x16x32_bf16 v[30:33], v[172:175], v[210:213], v[30:33]
	v_mfma_f32_16x16x32_bf16 v[22:25], v[180:183], v[210:213], v[22:25]
	v_mfma_f32_16x16x32_bf16 v[14:17], v[172:175], v[218:221], v[14:17]
	v_mfma_f32_16x16x32_bf16 v[10:13], v[180:183], v[218:221], v[10:13]
	v_mfma_f32_16x16x32_bf16 v[6:9], v[172:175], v[226:229], v[6:9]
	v_mfma_f32_16x16x32_bf16 v[2:5], v[180:183], v[226:229], v[2:5]
	s_barrier
	s_add_i32 s79, s79, 2
	s_add_u32 s41, s41, 0x100
	s_addc_u32 s70, s70, 0
	s_cmp_gt_u32 s79, 5
	s_mov_b64 s[80:81], vcc
	s_cbranch_scc0 .LBB0_125
	v_readlane_b32 s16, v254, 43
	s_and_b64 vcc, exec, s[20:21]
	v_readlane_b32 s33, v254, 40
	v_readlane_b32 s17, v254, 44
	v_readlane_b32 s77, v254, 46
	s_movk_i32 s79, 0x4000
	s_mov_b32 s70, 0x3a000000
	s_cbranch_vccz .LBB0_128
	s_barrier
; #define PG8_WAIT_V(n) asm volatile("s_waitcnt vmcnt(" #n ")" ::: "memory")
; #define PG8_BAR __builtin_amdgcn_s_barrier()
;     __device__ __forceinline__ void operator()(const f32x4 (&acc)[2][2][4][2], const Unit& u, int wr, int wc, int fr, int fq) const {
;         float* base = P + ((size_t)u.kp * 512 + (size_t)(u.pm - NTOK / BM) * BM + wr * 64 + fr) * D + u.pn * BM + wc * 32 + 4 * fq;
; #pragma unroll
;         for (int ai = 0; ai < 2; ++ai)
; #pragma unroll
;             for (int m = 0; m < 4; ++m)
; #pragma unroll
;                 for (int bj = 0; bj < 2; ++bj)
; #pragma unroll
;                     for (int n = 0; n < 2; ++n) *(f32x4*)(base + (size_t)(ai * HALF + m * 16) * D + bj * HALF + n * 16) = acc[ai][bj][m][n];
;     }
; template <class Epi, class Sched = StaticOrder, bool ALIGN_EPI = true>
; __device__ __forceinline__ void gemm_phase(LAS unsigned char* lds, const Gemm g, const Sched& S, const Epi& E) {
;     ...
;         if (!has_next) break;
; #pragma unroll
;         for (int a = 0; a < 2; ++a)
; #pragma unroll
;             for (int b = 0; b < 2; ++b)
; #pragma unroll
;                 for (int m = 0; m < 4; ++m)
; #pragma unroll
;                     for (int n = 0; n < 2; ++n) acc[a][b][m][n] = (f32x4){0.f, 0.f, 0.f, 0.f};
;         cur = nxt; cA = nA; cB = nB; ++ui;
;         if constexpr (ALIGN_EPI) { if (wr == 1) PG8_BAR; }
;     }
;     PG8_WAIT_V(0);
;     if constexpr (!ALIGN_EPI) { if (wr == 0) PG8_BAR; }
;     PG8_BAR;
.LBB0_128:
	s_ashr_i32 s13, s12, 31
	s_lshl_b64 s[0:1], s[12:13], 21
	s_lshl_b32 s11, s11, 22
	v_readlane_b32 s12, v253, 21
	s_add_u32 s0, s12, s0
	v_readlane_b32 s12, v253, 22
	s_addc_u32 s1, s12, s1
	s_add_u32 s0, s0, s11
	s_addc_u32 s1, s1, 0
	v_lshl_add_u64 v[144:145], s[0:1], 0, v[134:135]
	s_lshl_b32 s18, s10, 8
	v_lshl_add_u64 v[144:145], s[18:19], 2, v[144:145]
	s_mov_b32 s41, s19
	v_lshl_add_u64 v[144:145], v[144:145], 0, s[40:41]
	v_mov_b32_e32 v141, v0
	v_lshl_add_u64 v[144:145], v[144:145], 0, v[140:141]
	s_mov_b32 s0, 0x20000
	global_store_dwordx4 v[144:145], v[126:129], off
	global_store_dwordx4 v[144:145], v[122:125], off offset:64
	global_store_dwordx4 v[144:145], v[106:109], off offset:512
	global_store_dwordx4 v[144:145], v[98:101], off offset:576
	s_nop 1
	v_add_co_u32_e32 v98, vcc, s0, v144
	s_mov_b32 s0, 0x40000
	s_nop 0
	v_addc_co_u32_e32 v99, vcc, 0, v145, vcc
	global_store_dwordx4 v[98:99], v[118:121], off
	global_store_dwordx4 v[98:99], v[114:117], off offset:64
	global_store_dwordx4 v[98:99], v[90:93], off offset:512
	global_store_dwordx4 v[98:99], v[82:85], off offset:576
	s_nop 1
	v_add_co_u32_e32 v82, vcc, s0, v144
	s_mov_b32 s0, 0x60000
	s_nop 0
	v_addc_co_u32_e32 v83, vcc, 0, v145, vcc
	global_store_dwordx4 v[82:83], v[110:113], off
	global_store_dwordx4 v[82:83], v[102:105], off offset:64
	global_store_dwordx4 v[82:83], v[78:81], off offset:512
	global_store_dwordx4 v[82:83], v[74:77], off offset:576
	s_nop 1
	v_add_co_u32_e32 v74, vcc, s0, v144
	s_mov_b32 s0, 0x100000
	s_nop 0
	v_addc_co_u32_e32 v75, vcc, 0, v145, vcc
	global_store_dwordx4 v[74:75], v[94:97], off
	global_store_dwordx4 v[74:75], v[86:89], off offset:64
	global_store_dwordx4 v[74:75], v[70:73], off offset:512
	global_store_dwordx4 v[74:75], v[66:69], off offset:576
	s_nop 1
	v_add_co_u32_e32 v66, vcc, s0, v144
	s_mov_b32 s0, 0x120000
	s_nop 0
	v_addc_co_u32_e32 v67, vcc, 0, v145, vcc
	global_store_dwordx4 v[66:67], v[62:65], off
	global_store_dwordx4 v[66:67], v[58:61], off offset:64
	global_store_dwordx4 v[66:67], v[46:49], off offset:512
	global_store_dwordx4 v[66:67], v[38:41], off offset:576
	s_nop 1
	v_add_co_u32_e32 v38, vcc, s0, v144
	s_mov_b32 s0, 0x140000
	s_nop 0
	v_addc_co_u32_e32 v39, vcc, 0, v145, vcc
	global_store_dwordx4 v[38:39], v[54:57], off
	global_store_dwordx4 v[38:39], v[50:53], off offset:64
	global_store_dwordx4 v[38:39], v[30:33], off offset:512
	global_store_dwordx4 v[38:39], v[22:25], off offset:576
	s_nop 1
	v_add_co_u32_e32 v22, vcc, s0, v144
	s_mov_b64 s[0:1], -1
	s_nop 0
	v_addc_co_u32_e32 v23, vcc, 0, v145, vcc
	global_store_dwordx4 v[22:23], v[42:45], off
	global_store_dwordx4 v[22:23], v[34:37], off offset:64
	global_store_dwordx4 v[22:23], v[14:17], off offset:512
	global_store_dwordx4 v[22:23], v[10:13], off offset:576
	s_nop 1
	v_add_co_u32_e32 v10, vcc, 0x160000, v144
	s_nop 1
	v_addc_co_u32_e32 v11, vcc, 0, v145, vcc
	s_andn2_b64 vcc, exec, s[42:43]
	global_store_dwordx4 v[10:11], v[26:29], off
	global_store_dwordx4 v[10:11], v[18:21], off offset:64
	global_store_dwordx4 v[10:11], v[6:9], off offset:512
	global_store_dwordx4 v[10:11], v[2:5], off offset:576
	s_cbranch_vccnz .LBB0_119
	s_andn2_b64 vcc, exec, s[2:3]
	s_cbranch_vccnz .LBB0_118
	s_barrier
	s_branch .LBB0_118
.LBB0_131:
	s_setprio 0
	s_waitcnt vmcnt(0)
	v_readlane_b32 s22, v254, 39
	v_readlane_b32 s23, v254, 45
	s_barrier
.LBB0_132:
	s_mov_b64 s[0:1], 0

;     __device__ bool next(int i, Unit& u) const { const int idx = i * G + c; if (idx >= 64) return false; u.kp = idx & 3; u.pn = (idx >> 2) & 7; u.pm = 192 + (idx >> 5); return true; }
; #define PG8_STAGE(bufoff, gbase, voff) do { _Pragma("unroll") for (int _i = 0; _i < 2; ++_i) \
;         __builtin_amdgcn_global_load_lds((const unsigned*)((const char*)(gbase) + (voff)[_i]), (LAS unsigned*)(lds + (bufoff) + ldsw + _i * 8192), 16, 0, 0); } while (0)
; #define PG8_WAIT_V(n) asm volatile("s_waitcnt vmcnt(" #n ")" ::: "memory")
; #define PG8_BAR __builtin_amdgcn_s_barrier()
; template <class Epi, class Sched = StaticOrder, bool ALIGN_EPI = true>
; __device__ __forceinline__ void gemm_phase(LAS unsigned char* lds, const Gemm g, const Sched& S, const Epi& E) {
;     ...
;     for (int i = 0; i < 2; ++i) { int R, C; stage_rc(tid * 16 + i * 8192, R, C); const int Rb = Epi::PERM ? ((R & ~31) + perm32(R & 31)) : R;
;         voffA[i] = (unsigned)(R * g.ld + C) * 2u; voffB[i] = (unsigned)(Rb * g.ld + C) * 2u; }
;     const size_t kstep = (size_t)(BK * 2);
;     const size_t hstep = (size_t)HALF * g.ld * 2;
;     const size_t tstep = 2 * hstep;
;     const unsigned ldsw = (unsigned)wid * 1024u;
;     const int aoff = lds_byte(wr * 64 + fr, fq * 8), boff = lds_byte(wc * 32 + fr, fq * 8);
;     ...
;     Unit cur, nxt; int ui = 0;
;     if (!S.next(0, cur)) return;
;     f32x4 acc[2][2][4][2];
; #pragma unroll
;     for (int a = 0; a < 2; ++a)
; #pragma unroll
;         for (int b = 0; b < 2; ++b)
; #pragma unroll
;             for (int m = 0; m < 4; ++m)
; #pragma unroll
;                 for (int n = 0; n < 2; ++n) acc[a][b][m][n] = (f32x4){0.f, 0.f, 0.f, 0.f};
;     bf16x8 At[4][2], B0[2][2], B1[2][2];
;     const char* cA = (const char*)g.A + (size_t)cur.pm * tstep + (size_t)cur.kp * K * 2; const char* cB = (const char*)g.Bt + (size_t)cur.pn * tstep + (size_t)cur.kp * K * 2;
;     PG8_STAGE(PG8_SB(0, 0), cB, voffB); PG8_STAGE(PG8_SB(0, 1), cB + hstep, voffB); PG8_STAGE(PG8_SA(0, 0), cA, voffA); PG8_STAGE(PG8_SA(0, 1), cA + hstep, voffA);
;     if (wr == 1) PG8_BAR;
;     PG8_WAIT_V(2); PG8_BAR;
;     PG8_STAGE(PG8_SB(1, 0), cB + kstep, voffB); PG8_STAGE(PG8_SA(1, 0), cA + kstep, voffA); PG8_STAGE(PG8_SB(1, 1), cB + hstep + kstep, voffB);
;     PG8_WAIT_V(6); PG8_BAR;
.LBB0_330:
	v_lshrrev_b32_e32 v18, 1, v16
	v_and_b32_e32 v18, 24, v18
	s_lshl_b32 s11, s11, 5
	v_and_b32_e32 v17, 15, v16
	v_lshlrev_b32_e32 v19, 1, v18
	v_lshlrev_b32_e32 v16, 2, v16
	s_and_b32 s20, s11, 0x60
	v_lshl_or_b32 v1, s18, 6, v17
	v_lshl_or_b32 v17, v17, 6, v19
	v_and_b32_e32 v16, 32, v16
	s_lshl_b32 s11, s20, 7
	s_add_i32 m0, s7, 0x18000
	v_lshl_add_u64 v[8:9], v[8:9], 0, s[34:35]
	s_sext_i32_i8 s23, s12
	s_lshl_b32 s12, s18, 13
	v_bitop3_b32 v144, v17, s11, v16 bitop3:0xde
	s_waitcnt vmcnt(2)
	s_barrier
	global_load_lds_dwordx4 v[8:9], off
	v_lshl_add_u64 v[6:7], v[6:7], 0, s[34:35]
	s_add_i32 m0, s7, 0x1a000
	s_add_i32 s11, s7, 0x8000
	s_add_i32 s18, s7, 0xa000
	global_load_lds_dwordx4 v[6:7], off
	v_lshl_add_u64 v[2:3], v[2:3], 0, s[34:35]
	s_mov_b32 m0, s11
	s_add_u32 s16, s92, 0x80080
	global_load_lds_dwordx4 v[2:3], off
	v_lshl_add_u64 v[2:3], v[4:5], 0, s[34:35]
	s_mov_b32 m0, s18
	s_addc_u32 s17, s93, 0
	global_load_lds_dwordx4 v[2:3], off
	s_add_i32 m0, s7, 0x1c000
	v_lshl_add_u64 v[2:3], s[16:17], 0, v[134:135]
	global_load_lds_dwordx4 v[2:3], off
	v_lshl_add_u64 v[2:3], s[16:17], 0, v[130:131]
	s_add_i32 m0, s7, 0x1e000
	v_bitop3_b32 v19, v17, s12, v16 bitop3:0xde
	global_load_lds_dwordx4 v[2:3], off
	v_lshlrev_b32_e32 v2, 15, v14
	v_and_b32_e32 v2, 0xffff0000, v2
	v_lshl_add_u32 v2, v13, 12, v2
	v_and_b32_e32 v3, 1, v14
	v_lshl_or_b32 v2, v3, 6, v2
	v_lshl_add_u32 v138, v15, 1, v2
	v_lshlrev_b32_e32 v2, 15, v10
	v_and_b32_e32 v2, 0xffff0000, v2
	s_waitcnt vmcnt(6)
	v_lshl_add_u32 v2, v11, 12, v2
	v_and_b32_e32 v3, 1, v10
	s_cmpk_lt_u32 s13, 0x100
	v_lshl_or_b32 v2, v3, 6, v2
	s_cselect_b64 s[12:13], -1, 0
	v_or_b32_e32 v145, s20, v18
	v_mov_b32_e32 v139, v0
	v_lshl_add_u32 v140, v12, 1, v2
	v_mov_b32_e32 v141, v0
	s_mov_b32 s22, 0
	v_add_u32_e32 v146, 0, v19
	s_barrier
	s_branch .LBB0_333

;     __device__ bool next(int i, Unit& u) const { const int idx = i * G + c; if (idx >= 64) return false; u.kp = idx & 3; u.pn = (idx >> 2) & 7; u.pm = 192 + (idx >> 5); return true; }
; #define PG8_STAGE(bufoff, gbase, voff) do { _Pragma("unroll") for (int _i = 0; _i < 2; ++_i) \
;         __builtin_amdgcn_global_load_lds((const unsigned*)((const char*)(gbase) + (voff)[_i]), (LAS unsigned*)(lds + (bufoff) + ldsw + _i * 8192), 16, 0, 0); } while (0)
; #define PG8_WAIT_V(n) asm volatile("s_waitcnt vmcnt(" #n ")" ::: "memory")
; #define PG8_BAR __builtin_amdgcn_s_barrier()
; template <class Epi, class Sched = StaticOrder, bool ALIGN_EPI = true>
; __device__ __forceinline__ void gemm_phase(LAS unsigned char* lds, const Gemm g, const Sched& S, const Epi& E) {
;     ...
;     for (int i = 0; i < 2; ++i) { int R, C; stage_rc(tid * 16 + i * 8192, R, C); const int Rb = Epi::PERM ? ((R & ~31) + perm32(R & 31)) : R;
;         voffA[i] = (unsigned)(R * g.ld + C) * 2u; voffB[i] = (unsigned)(Rb * g.ld + C) * 2u; }
;     const size_t kstep = (size_t)(BK * 2);
;     const size_t hstep = (size_t)HALF * g.ld * 2;
;     const size_t tstep = 2 * hstep;
;     const unsigned ldsw = (unsigned)wid * 1024u;
;     const int aoff = lds_byte(wr * 64 + fr, fq * 8), boff = lds_byte(wc * 32 + fr, fq * 8);
;     ...
;     Unit cur, nxt; int ui = 0;
;     if (!S.next(0, cur)) return;
;     f32x4 acc[2][2][4][2];
; #pragma unroll
;     for (int a = 0; a < 2; ++a)
; #pragma unroll
;         for (int b = 0; b < 2; ++b)
; #pragma unroll
;             for (int m = 0; m < 4; ++m)
; #pragma unroll
;                 for (int n = 0; n < 2; ++n) acc[a][b][m][n] = (f32x4){0.f, 0.f, 0.f, 0.f};
;     bf16x8 At[4][2], B0[2][2], B1[2][2];
;     const char* cA = (const char*)g.A + (size_t)cur.pm * tstep + (size_t)cur.kp * K * 2; const char* cB = (const char*)g.Bt + (size_t)cur.pn * tstep + (size_t)cur.kp * K * 2;
;     PG8_STAGE(PG8_SB(0, 0), cB, voffB); PG8_STAGE(PG8_SB(0, 1), cB + hstep, voffB); PG8_STAGE(PG8_SA(0, 0), cA, voffA); PG8_STAGE(PG8_SA(0, 1), cA + hstep, voffA);
;     if (wr == 1) PG8_BAR;
;     PG8_WAIT_V(2); PG8_BAR;
;     PG8_STAGE(PG8_SB(1, 0), cB + kstep, voffB); PG8_STAGE(PG8_SA(1, 0), cA + kstep, voffA); PG8_STAGE(PG8_SB(1, 1), cB + hstep + kstep, voffB);
;     PG8_WAIT_V(6); PG8_BAR;
.LBB0_360:
	v_lshrrev_b32_e32 v20, 1, v18
	v_and_b32_e32 v20, 24, v20
	v_and_b32_e32 v19, 15, v18
	v_lshlrev_b32_e32 v21, 1, v20
	v_lshlrev_b32_e32 v18, 2, v18
	s_lshl_b32 s1, s1, 5
	v_lshl_or_b32 v1, s10, 6, v19
	v_lshl_or_b32 v19, v19, 6, v21
	s_lshl_b32 s10, s10, 13
	v_and_b32_e32 v18, 32, v18
	s_and_b32 s1, s1, 0x60
	v_bitop3_b32 v21, v19, s10, v18 bitop3:0xde
	s_lshl_b32 s10, s1, 7
	s_add_i32 m0, s6, 0x18000
	v_lshl_add_u64 v[8:9], v[8:9], 0, s[34:35]
	s_sext_i32_i8 s70, s11
	v_bitop3_b32 v144, v19, s10, v18 bitop3:0xde
	s_waitcnt vmcnt(2)
	s_barrier
	global_load_lds_dwordx4 v[8:9], off
	v_lshl_add_u64 v[6:7], v[6:7], 0, s[34:35]
	s_add_i32 m0, s6, 0x1a000
	s_add_i32 s10, s6, 0x8000
	s_add_i32 s11, s6, 0xa000
	global_load_lds_dwordx4 v[6:7], off
	v_lshl_add_u64 v[2:3], v[2:3], 0, s[34:35]
	s_mov_b32 m0, s10
	s_add_u32 s16, s46, 0x160080
	global_load_lds_dwordx4 v[2:3], off
	v_lshl_add_u64 v[2:3], v[4:5], 0, s[34:35]
	s_mov_b32 m0, s11
	s_addc_u32 s17, s47, 0
	global_load_lds_dwordx4 v[2:3], off
	s_add_i32 m0, s6, 0x1c000
	v_lshl_add_u64 v[2:3], s[16:17], 0, v[134:135]
	global_load_lds_dwordx4 v[2:3], off
	v_lshl_add_u64 v[2:3], s[16:17], 0, v[130:131]
	s_add_i32 m0, s6, 0x1e000
	s_movk_i32 s17, 0x1600
	global_load_lds_dwordx4 v[2:3], off
	v_lshrrev_b32_e32 v3, 1, v15
	v_mul_lo_u32 v2, v14, s17
	s_mov_b32 s16, 0x16000
	s_cmpk_lt_u32 s0, 0x100
	v_or_b32_e32 v145, s1, v20
	v_mad_u64_u32 v[2:3], s[0:1], v3, s16, v[2:3]
	v_or_b32_e32 v2, v2, v16
	v_add_lshl_u32 v2, v2, v17, 1
	v_mov_b32_e32 v3, v0
	s_mov_b64 s[22:23], 0x160080
	v_lshl_add_u64 v[138:139], v[2:3], 0, s[22:23]
	v_lshrrev_b32_e32 v3, 1, v10
	v_mul_lo_u32 v2, v11, s17
	v_mad_u64_u32 v[2:3], s[0:1], v3, s16, v[2:3]
	s_waitcnt vmcnt(6)
	v_or_b32_e32 v2, v2, v12
	v_add_lshl_u32 v2, v2, v13, 1
	v_mov_b32_e32 v3, v0
	s_cselect_b64 s[20:21], -1, 0
	v_lshl_add_u64 v[140:141], v[2:3], 0, s[22:23]
	s_mov_b32 s22, 0
	v_add_u32_e32 v146, 0, v21
	s_barrier
	s_branch .LBB0_363

; #define PG8_STAGE(bufoff, gbase, voff) do { _Pragma("unroll") for (int _i = 0; _i < 2; ++_i) \
;         __builtin_amdgcn_global_load_lds((const unsigned*)((const char*)(gbase) + (voff)[_i]), (LAS unsigned*)(lds + (bufoff) + ldsw + _i * 8192), 16, 0, 0); } while (0)
; #define PG8_LDA(dst, b, h) do { _Pragma("unroll") for (int m = 0; m < 4; ++m) _Pragma("unroll") for (int k = 0; k < 2; ++k) dst[m][k] = *(const LAS bf16x8*)(lds + PG8_SA(b, h) + aoff + m * 2048 + k * 1024); } while (0)
; #define PG8_LDB(dst, b, h) do { _Pragma("unroll") for (int n = 0; n < 2; ++n) _Pragma("unroll") for (int k = 0; k < 2; ++k) dst[n][k] = *(const LAS bf16x8*)(lds + PG8_SB(b, h) + boff + n * 2048 + k * 1024); } while (0)
; #define PG8_WAIT_V(n) asm volatile("s_waitcnt vmcnt(" #n ")" ::: "memory")
; template <class Epi, class Sched = StaticOrder, bool ALIGN_EPI = true>
; __device__ __forceinline__ void gemm_phase(LAS unsigned char* lds, const Gemm g, const Sched& S, const Epi& E) {
;     ...
;         for (int t = 0; t < nt; t += 2) {
;             const bool last = (t == nt - 2);
;             const char* a1 = cA + (size_t)(t + 1) * kstep;
;             const char* a2 = last ? nA : cA + (size_t)(t + 2) * kstep; const char* b2 = last ? nB : cB + (size_t)(t + 2) * kstep;
;             const char* a3 = a2 + kstep; const char* b3 = b2 + kstep;
;             PG8_LDB(B0, 0, 0); PG8_LDB(B1, 0, 1); PG8_SCHED; PG8_LDA(At, 0, 0); PG8_STAGE(PG8_SA(1, 1), a1 + hstep, voffA);
;             PG8_WAIT_V(8); PG8_WAIT_L(0); PG8_BAR; PG8_MMA(0, 0, At, B0); PG8_MMA(0, 1, At, B1); PG8_BAR; PG8_SCHED;
;             PG8_LDA(At, 0, 1); PG8_STAGE(PG8_SB(0, 0), b2, voffB); PG8_STAGE(PG8_SB(0, 1), b2 + hstep, voffB); PG8_STAGE(PG8_SA(0, 0), a2, voffA);
;             PG8_WAIT_V(8); PG8_WAIT_L(0); PG8_BAR; PG8_MMA(1, 0, At, B0); PG8_MMA(1, 1, At, B1); PG8_BAR; PG8_SCHED;
;             PG8_LDB(B0, 1, 0); PG8_LDB(B1, 1, 1); PG8_SCHED; PG8_LDA(At, 1, 0); PG8_STAGE(PG8_SA(0, 1), a2 + hstep, voffA);
;             PG8_WAIT_V(8); PG8_WAIT_L(0); PG8_BAR; PG8_MMA(0, 0, At, B0); PG8_MMA(0, 1, At, B1); PG8_BAR; PG8_SCHED;
;             PG8_LDA(At, 1, 1); PG8_STAGE(PG8_SB(1, 0), b3, voffB); PG8_STAGE(PG8_SB(1, 1), b3 + hstep, voffB); PG8_STAGE(PG8_SA(1, 0), a3, voffA);
;             PG8_WAIT_V(8); PG8_WAIT_L(0); PG8_BAR; PG8_MMA(1, 0, At, B0); PG8_MMA(1, 1, At, B1); PG8_BAR; PG8_SCHED;
.LBB0_411:
	s_add_u32 s48, s46, 0x100
	s_addc_u32 s49, s47, 0
	s_add_i32 s16, 0, 0x10000
	s_cmp_eq_u32 s37, 18
	s_cselect_b32 s31, s43, s49
	s_cselect_b32 s30, s42, s48
	v_add_u32_e32 v141, s16, v1
	s_cselect_b32 s1, s45, s18
	s_cselect_b32 s0, s44, s3
	s_add_i32 s33, 0, 0x14000
	ds_read_b128 v[144:147], v141
	ds_read_b128 v[148:151], v141 offset:1024
	ds_read_b128 v[160:163], v141 offset:2048
	ds_read_b128 v[164:167], v141 offset:3072
	v_add_u32_e32 v141, s33, v1
	ds_read_b128 v[168:171], v141
	ds_read_b128 v[172:175], v141 offset:1024
	ds_read_b128 v[176:179], v141 offset:2048
	ds_read_b128 v[180:183], v141 offset:3072
	v_lshl_add_u64 v[152:153], s[46:47], 0, v[136:137]
	s_add_i32 m0, s6, 0xc000
	ds_read_b128 v[184:187], v142
	ds_read_b128 v[188:191], v142 offset:1024
	ds_read_b128 v[192:195], v142 offset:2048
	ds_read_b128 v[210:213], v142 offset:3072
	ds_read_b128 v[214:217], v142 offset:4096
	ds_read_b128 v[218:221], v142 offset:5120
	ds_read_b128 v[222:225], v142 offset:6144
	ds_read_b128 v[226:229], v142 offset:7168
	global_load_lds_dwordx4 v[152:153], off
	s_add_i32 m0, s6, 0xe000
	v_lshl_add_u64 v[152:153], s[46:47], 0, v[138:139]
	global_load_lds_dwordx4 v[152:153], off
	s_waitcnt vmcnt(8) lgkmcnt(0)
	s_barrier
	v_mfma_f32_16x16x32_bf16 v[126:129], v[144:147], v[184:187], v[126:129]
	v_mfma_f32_16x16x32_bf16 v[122:125], v[160:163], v[184:187], v[122:125]
	v_mfma_f32_16x16x32_bf16 v[118:121], v[144:147], v[192:195], v[118:121]
	v_mfma_f32_16x16x32_bf16 v[114:117], v[160:163], v[192:195], v[114:117]
	v_mfma_f32_16x16x32_bf16 v[110:113], v[144:147], v[214:217], v[110:113]
	v_mfma_f32_16x16x32_bf16 v[102:105], v[160:163], v[214:217], v[102:105]
	v_mfma_f32_16x16x32_bf16 v[94:97], v[144:147], v[222:225], v[94:97]
	v_mfma_f32_16x16x32_bf16 v[86:89], v[160:163], v[222:225], v[86:89]
	v_mfma_f32_16x16x32_bf16 v[126:129], v[148:151], v[188:191], v[126:129]
	v_mfma_f32_16x16x32_bf16 v[122:125], v[164:167], v[188:191], v[122:125]
	v_mfma_f32_16x16x32_bf16 v[118:121], v[148:151], v[210:213], v[118:121]
	v_mfma_f32_16x16x32_bf16 v[114:117], v[164:167], v[210:213], v[114:117]
	v_mfma_f32_16x16x32_bf16 v[110:113], v[148:151], v[218:221], v[110:113]
	v_mfma_f32_16x16x32_bf16 v[102:105], v[164:167], v[218:221], v[102:105]
	v_mfma_f32_16x16x32_bf16 v[94:97], v[148:151], v[226:229], v[94:97]
	v_mfma_f32_16x16x32_bf16 v[86:89], v[164:167], v[226:229], v[86:89]
	v_mfma_f32_16x16x32_bf16 v[106:109], v[168:171], v[184:187], v[106:109]
	v_mfma_f32_16x16x32_bf16 v[98:101], v[176:179], v[184:187], v[98:101]
	v_mfma_f32_16x16x32_bf16 v[90:93], v[168:171], v[192:195], v[90:93]
	v_mfma_f32_16x16x32_bf16 v[82:85], v[176:179], v[192:195], v[82:85]
	v_mfma_f32_16x16x32_bf16 v[78:81], v[168:171], v[214:217], v[78:81]
	v_mfma_f32_16x16x32_bf16 v[74:77], v[176:179], v[214:217], v[74:77]
	v_mfma_f32_16x16x32_bf16 v[70:73], v[168:171], v[222:225], v[70:73]
	v_mfma_f32_16x16x32_bf16 v[66:69], v[176:179], v[222:225], v[66:69]
	v_mfma_f32_16x16x32_bf16 v[106:109], v[172:175], v[188:191], v[106:109]
	v_mfma_f32_16x16x32_bf16 v[98:101], v[180:183], v[188:191], v[98:101]
	v_mfma_f32_16x16x32_bf16 v[90:93], v[172:175], v[210:213], v[90:93]
	v_mfma_f32_16x16x32_bf16 v[82:85], v[180:183], v[210:213], v[82:85]
	v_mfma_f32_16x16x32_bf16 v[78:81], v[172:175], v[218:221], v[78:81]
	v_mfma_f32_16x16x32_bf16 v[74:77], v[180:183], v[218:221], v[74:77]
	v_mfma_f32_16x16x32_bf16 v[70:73], v[172:175], v[226:229], v[70:73]
	v_mfma_f32_16x16x32_bf16 v[66:69], v[180:183], v[226:229], v[66:69]
	s_barrier
	s_add_i32 s16, s16, s5
	v_lshl_add_u64 v[152:153], s[0:1], 0, v[132:133]
	s_mov_b32 m0, s16
	ds_read_b128 v[184:187], v142 offset:16384
	ds_read_b128 v[188:191], v142 offset:17408
	ds_read_b128 v[192:195], v142 offset:18432
	ds_read_b128 v[210:213], v142 offset:19456
	ds_read_b128 v[214:217], v142 offset:20480
	ds_read_b128 v[218:221], v142 offset:21504
	ds_read_b128 v[222:225], v142 offset:22528
	ds_read_b128 v[226:229], v142 offset:23552
	global_load_lds_dwordx4 v[152:153], off
	s_add_i32 m0, s16, 0x2000
	s_add_u32 s16, s0, 0x160000
	v_lshl_add_u64 v[196:197], s[0:1], 0, v[130:131]
	s_addc_u32 s17, s1, 0
	s_add_i32 s33, s33, s5
	global_load_lds_dwordx4 v[196:197], off
	v_lshl_add_u64 v[230:231], s[16:17], 0, v[132:133]
	s_mov_b32 m0, s33
	v_lshl_add_u64 v[232:233], s[30:31], 0, v[130:131]
	global_load_lds_dwordx4 v[230:231], off
	s_add_i32 m0, s33, 0x2000
	v_lshl_add_u64 v[230:231], s[16:17], 0, v[130:131]
	global_load_lds_dwordx4 v[230:231], off
	s_mov_b32 m0, s6
	v_lshl_add_u64 v[230:231], s[30:31], 0, v[132:133]
	global_load_lds_dwordx4 v[230:231], off
	s_mov_b32 m0, s7
	s_nop 0
	global_load_lds_dwordx4 v[232:233], off
	s_waitcnt vmcnt(8) lgkmcnt(0)
	s_barrier
; #define PG8_STAGE(bufoff, gbase, voff) do { _Pragma("unroll") for (int _i = 0; _i < 2; ++_i) \
;         __builtin_amdgcn_global_load_lds((const unsigned*)((const char*)(gbase) + (voff)[_i]), (LAS unsigned*)(lds + (bufoff) + ldsw + _i * 8192), 16, 0, 0); } while (0)
; #define PG8_LDA(dst, b, h) do { _Pragma("unroll") for (int m = 0; m < 4; ++m) _Pragma("unroll") for (int k = 0; k < 2; ++k) dst[m][k] = *(const LAS bf16x8*)(lds + PG8_SA(b, h) + aoff + m * 2048 + k * 1024); } while (0)
; #define PG8_LDB(dst, b, h) do { _Pragma("unroll") for (int n = 0; n < 2; ++n) _Pragma("unroll") for (int k = 0; k < 2; ++k) dst[n][k] = *(const LAS bf16x8*)(lds + PG8_SB(b, h) + boff + n * 2048 + k * 1024); } while (0)
; #define PG8_MMA(ai, bj, At, Bt) do { __builtin_amdgcn_s_setprio(1); _Pragma("unroll") for (int m = 0; m < 4; ++m) _Pragma("unroll") for (int n = 0; n < 2; ++n) _Pragma("unroll") for (int k = 0; k < 2; ++k) \
;         acc[ai][bj][m][n] = __builtin_amdgcn_mfma_f32_16x16x32_bf16(Bt[n][k], At[m][k], acc[ai][bj][m][n], 0, 0, 0); __builtin_amdgcn_s_setprio(0); } while (0)
; #define PG8_WAIT_V(n) asm volatile("s_waitcnt vmcnt(" #n ")" ::: "memory")
; #define PG8_WAIT_L(n) asm volatile("s_waitcnt lgkmcnt(" #n ")" ::: "memory")
; #define PG8_BAR __builtin_amdgcn_s_barrier()
; #define PG8_SCHED __builtin_amdgcn_sched_barrier(0)
; template <class Epi, class Sched = StaticOrder, bool ALIGN_EPI = true>
; __device__ __forceinline__ void gemm_phase(LAS unsigned char* lds, const Gemm g, const Sched& S, const Epi& E) {
;     ...
;             PG8_WAIT_V(8); PG8_WAIT_L(0); PG8_BAR; PG8_MMA(1, 0, At, B0); PG8_MMA(1, 1, At, B1); PG8_BAR; PG8_SCHED;
;             PG8_LDB(B0, 1, 0); PG8_LDB(B1, 1, 1); PG8_SCHED; PG8_LDA(At, 1, 0); PG8_STAGE(PG8_SA(0, 1), a2 + hstep, voffA);
;             PG8_WAIT_V(8); PG8_WAIT_L(0); PG8_BAR; PG8_MMA(0, 0, At, B0); PG8_MMA(0, 1, At, B1); PG8_BAR; PG8_SCHED;
;             PG8_LDA(At, 1, 1); PG8_STAGE(PG8_SB(1, 0), b3, voffB); PG8_STAGE(PG8_SB(1, 1), b3 + hstep, voffB); PG8_STAGE(PG8_SA(1, 0), a3, voffA);
	v_mfma_f32_16x16x32_bf16 v[62:65], v[144:147], v[184:187], v[62:65]
	v_mfma_f32_16x16x32_bf16 v[58:61], v[160:163], v[184:187], v[58:61]
	v_mfma_f32_16x16x32_bf16 v[54:57], v[144:147], v[192:195], v[54:57]
	v_mfma_f32_16x16x32_bf16 v[50:53], v[160:163], v[192:195], v[50:53]
	v_mfma_f32_16x16x32_bf16 v[42:45], v[144:147], v[214:217], v[42:45]
	v_mfma_f32_16x16x32_bf16 v[34:37], v[160:163], v[214:217], v[34:37]
	v_mfma_f32_16x16x32_bf16 v[26:29], v[144:147], v[222:225], v[26:29]
	v_mfma_f32_16x16x32_bf16 v[18:21], v[160:163], v[222:225], v[18:21]
	v_mfma_f32_16x16x32_bf16 v[62:65], v[148:151], v[188:191], v[62:65]
	v_mfma_f32_16x16x32_bf16 v[58:61], v[164:167], v[188:191], v[58:61]
	v_mfma_f32_16x16x32_bf16 v[54:57], v[148:151], v[210:213], v[54:57]
	v_mfma_f32_16x16x32_bf16 v[50:53], v[164:167], v[210:213], v[50:53]
	v_mfma_f32_16x16x32_bf16 v[42:45], v[148:151], v[218:221], v[42:45]
	v_mfma_f32_16x16x32_bf16 v[34:37], v[164:167], v[218:221], v[34:37]
	v_mfma_f32_16x16x32_bf16 v[26:29], v[148:151], v[226:229], v[26:29]
	v_mfma_f32_16x16x32_bf16 v[18:21], v[164:167], v[226:229], v[18:21]
	v_mfma_f32_16x16x32_bf16 v[46:49], v[168:171], v[184:187], v[46:49]
	v_mfma_f32_16x16x32_bf16 v[38:41], v[176:179], v[184:187], v[38:41]
	v_mfma_f32_16x16x32_bf16 v[30:33], v[168:171], v[192:195], v[30:33]
	v_mfma_f32_16x16x32_bf16 v[22:25], v[176:179], v[192:195], v[22:25]
	v_mfma_f32_16x16x32_bf16 v[14:17], v[168:171], v[214:217], v[14:17]
	v_mfma_f32_16x16x32_bf16 v[10:13], v[176:179], v[214:217], v[10:13]
	v_mfma_f32_16x16x32_bf16 v[6:9], v[168:171], v[222:225], v[6:9]
	v_mfma_f32_16x16x32_bf16 v[2:5], v[176:179], v[222:225], v[2:5]
	v_mfma_f32_16x16x32_bf16 v[46:49], v[172:175], v[188:191], v[46:49]
	v_mfma_f32_16x16x32_bf16 v[38:41], v[180:183], v[188:191], v[38:41]
	v_mfma_f32_16x16x32_bf16 v[30:33], v[172:175], v[210:213], v[30:33]
	v_mfma_f32_16x16x32_bf16 v[22:25], v[180:183], v[210:213], v[22:25]
	v_mfma_f32_16x16x32_bf16 v[14:17], v[172:175], v[218:221], v[14:17]
	v_mfma_f32_16x16x32_bf16 v[10:13], v[180:183], v[218:221], v[10:13]
	v_mfma_f32_16x16x32_bf16 v[6:9], v[172:175], v[226:229], v[6:9]
	v_mfma_f32_16x16x32_bf16 v[2:5], v[180:183], v[226:229], v[2:5]
	s_barrier
	s_add_i32 s33, 0, 0x18000
	v_add_u32_e32 v141, s33, v1
	s_add_i32 s46, 0, 0x1c000
	ds_read_b128 v[144:147], v141
	ds_read_b128 v[148:151], v141 offset:1024
	ds_read_b128 v[160:163], v141 offset:2048
	ds_read_b128 v[164:167], v141 offset:3072
	v_add_u32_e32 v141, s46, v1
	ds_read_b128 v[168:171], v141
	ds_read_b128 v[172:175], v141 offset:1024
	ds_read_b128 v[176:179], v141 offset:2048
	ds_read_b128 v[180:183], v141 offset:3072
	s_add_u32 s16, s30, 0x160000
	s_addc_u32 s17, s31, 0
	s_mov_b32 m0, s9
	v_lshl_add_u64 v[234:235], s[16:17], 0, v[132:133]
	ds_read_b128 v[184:187], v142 offset:32768
	ds_read_b128 v[188:191], v142 offset:33792
	ds_read_b128 v[192:195], v142 offset:34816
	ds_read_b128 v[210:213], v142 offset:35840
	ds_read_b128 v[214:217], v142 offset:36864
	ds_read_b128 v[218:221], v142 offset:37888
	ds_read_b128 v[222:225], v142 offset:38912
	ds_read_b128 v[226:229], v142 offset:39936
	global_load_lds_dwordx4 v[234:235], off
	s_mov_b32 m0, s10
	v_lshl_add_u64 v[234:235], s[16:17], 0, v[130:131]
	global_load_lds_dwordx4 v[234:235], off
	s_waitcnt vmcnt(8) lgkmcnt(0)
	s_barrier
	v_mfma_f32_16x16x32_bf16 v[126:129], v[144:147], v[184:187], v[126:129]
	v_mfma_f32_16x16x32_bf16 v[122:125], v[160:163], v[184:187], v[122:125]
	v_mfma_f32_16x16x32_bf16 v[118:121], v[144:147], v[192:195], v[118:121]
	v_mfma_f32_16x16x32_bf16 v[114:117], v[160:163], v[192:195], v[114:117]
	v_mfma_f32_16x16x32_bf16 v[110:113], v[144:147], v[214:217], v[110:113]
	v_mfma_f32_16x16x32_bf16 v[102:105], v[160:163], v[214:217], v[102:105]
	v_mfma_f32_16x16x32_bf16 v[94:97], v[144:147], v[222:225], v[94:97]
	v_mfma_f32_16x16x32_bf16 v[86:89], v[160:163], v[222:225], v[86:89]
	v_mfma_f32_16x16x32_bf16 v[126:129], v[148:151], v[188:191], v[126:129]
	v_mfma_f32_16x16x32_bf16 v[122:125], v[164:167], v[188:191], v[122:125]
	v_mfma_f32_16x16x32_bf16 v[118:121], v[148:151], v[210:213], v[118:121]
	v_mfma_f32_16x16x32_bf16 v[114:117], v[164:167], v[210:213], v[114:117]
	v_mfma_f32_16x16x32_bf16 v[110:113], v[148:151], v[218:221], v[110:113]
	v_mfma_f32_16x16x32_bf16 v[102:105], v[164:167], v[218:221], v[102:105]
	v_mfma_f32_16x16x32_bf16 v[94:97], v[148:151], v[226:229], v[94:97]
	v_mfma_f32_16x16x32_bf16 v[86:89], v[164:167], v[226:229], v[86:89]
	v_mfma_f32_16x16x32_bf16 v[106:109], v[168:171], v[184:187], v[106:109]
	v_mfma_f32_16x16x32_bf16 v[98:101], v[176:179], v[184:187], v[98:101]
	v_mfma_f32_16x16x32_bf16 v[90:93], v[168:171], v[192:195], v[90:93]
	v_mfma_f32_16x16x32_bf16 v[82:85], v[176:179], v[192:195], v[82:85]
	v_mfma_f32_16x16x32_bf16 v[78:81], v[168:171], v[214:217], v[78:81]
	v_mfma_f32_16x16x32_bf16 v[74:77], v[176:179], v[214:217], v[74:77]
	v_mfma_f32_16x16x32_bf16 v[70:73], v[168:171], v[222:225], v[70:73]
	v_mfma_f32_16x16x32_bf16 v[66:69], v[176:179], v[222:225], v[66:69]
	v_mfma_f32_16x16x32_bf16 v[106:109], v[172:175], v[188:191], v[106:109]
	v_mfma_f32_16x16x32_bf16 v[98:101], v[180:183], v[188:191], v[98:101]
	v_mfma_f32_16x16x32_bf16 v[90:93], v[172:175], v[210:213], v[90:93]
	v_mfma_f32_16x16x32_bf16 v[82:85], v[180:183], v[210:213], v[82:85]
	v_mfma_f32_16x16x32_bf16 v[78:81], v[172:175], v[218:221], v[78:81]
	v_mfma_f32_16x16x32_bf16 v[74:77], v[180:183], v[218:221], v[74:77]
	v_mfma_f32_16x16x32_bf16 v[70:73], v[172:175], v[226:229], v[70:73]
	v_mfma_f32_16x16x32_bf16 v[66:69], v[180:183], v[226:229], v[66:69]
	s_barrier
; #define PG8_STAGE(bufoff, gbase, voff) do { _Pragma("unroll") for (int _i = 0; _i < 2; ++_i) \
;         __builtin_amdgcn_global_load_lds((const unsigned*)((const char*)(gbase) + (voff)[_i]), (LAS unsigned*)(lds + (bufoff) + ldsw + _i * 8192), 16, 0, 0); } while (0)
; #define PG8_LDA(dst, b, h) do { _Pragma("unroll") for (int m = 0; m < 4; ++m) _Pragma("unroll") for (int k = 0; k < 2; ++k) dst[m][k] = *(const LAS bf16x8*)(lds + PG8_SA(b, h) + aoff + m * 2048 + k * 1024); } while (0)
; #define PG8_MMA(ai, bj, At, Bt) do { __builtin_amdgcn_s_setprio(1); _Pragma("unroll") for (int m = 0; m < 4; ++m) _Pragma("unroll") for (int n = 0; n < 2; ++n) _Pragma("unroll") for (int k = 0; k < 2; ++k) \
;         acc[ai][bj][m][n] = __builtin_amdgcn_mfma_f32_16x16x32_bf16(Bt[n][k], At[m][k], acc[ai][bj][m][n], 0, 0, 0); __builtin_amdgcn_s_setprio(0); } while (0)
; #define PG8_WAIT_V(n) asm volatile("s_waitcnt vmcnt(" #n ")" ::: "memory")
; #define PG8_WAIT_L(n) asm volatile("s_waitcnt lgkmcnt(" #n ")" ::: "memory")
; #define PG8_BAR __builtin_amdgcn_s_barrier()
; #define PG8_SCHED __builtin_amdgcn_sched_barrier(0)
; template <class Epi, class Sched = StaticOrder, bool ALIGN_EPI = true>
; __device__ __forceinline__ void gemm_phase(LAS unsigned char* lds, const Gemm g, const Sched& S, const Epi& E) {
;     ...
;             PG8_LDA(At, 1, 1); PG8_STAGE(PG8_SB(1, 0), b3, voffB); PG8_STAGE(PG8_SB(1, 1), b3 + hstep, voffB); PG8_STAGE(PG8_SA(1, 0), a3, voffA);
;             PG8_WAIT_V(8); PG8_WAIT_L(0); PG8_BAR; PG8_MMA(1, 0, At, B0); PG8_MMA(1, 1, At, B1); PG8_BAR; PG8_SCHED;
;         }
;         if constexpr (ALIGN_EPI) { if (wr == 0) PG8_BAR; }
	s_add_i32 s16, s33, s5
	v_lshl_add_u64 v[152:153], v[152:153], 0, s[34:35]
	s_mov_b32 m0, s16
	ds_read_b128 v[184:187], v142 offset:49152
	ds_read_b128 v[188:191], v142 offset:50176
	ds_read_b128 v[192:195], v142 offset:51200
	ds_read_b128 v[210:213], v142 offset:52224
	ds_read_b128 v[214:217], v142 offset:53248
	ds_read_b128 v[218:221], v142 offset:54272
	ds_read_b128 v[222:225], v142 offset:55296
	ds_read_b128 v[226:229], v142 offset:56320
	global_load_lds_dwordx4 v[152:153], off
	s_add_i32 m0, s16, 0x2000
	s_add_u32 s0, s0, 0x160080
	v_lshl_add_u64 v[152:153], v[196:197], 0, s[34:35]
	s_addc_u32 s1, s1, 0
	s_add_i32 s16, s46, s5
	global_load_lds_dwordx4 v[152:153], off
	s_mov_b32 m0, s16
	v_lshl_add_u64 v[152:153], s[0:1], 0, v[132:133]
	global_load_lds_dwordx4 v[152:153], off
	s_add_i32 m0, s16, 0x2000
	v_lshl_add_u64 v[152:153], s[0:1], 0, v[130:131]
	global_load_lds_dwordx4 v[152:153], off
	s_mov_b32 m0, s22
	v_lshl_add_u64 v[152:153], v[230:231], 0, s[34:35]
	global_load_lds_dwordx4 v[152:153], off
	s_mov_b32 m0, s23
	v_lshl_add_u64 v[152:153], v[232:233], 0, s[34:35]
	global_load_lds_dwordx4 v[152:153], off
	s_waitcnt vmcnt(8) lgkmcnt(0)
	s_barrier
	v_mfma_f32_16x16x32_bf16 v[62:65], v[144:147], v[184:187], v[62:65]
	v_mfma_f32_16x16x32_bf16 v[58:61], v[160:163], v[184:187], v[58:61]
	v_mfma_f32_16x16x32_bf16 v[54:57], v[144:147], v[192:195], v[54:57]
	v_mfma_f32_16x16x32_bf16 v[50:53], v[160:163], v[192:195], v[50:53]
	v_mfma_f32_16x16x32_bf16 v[42:45], v[144:147], v[214:217], v[42:45]
	v_mfma_f32_16x16x32_bf16 v[34:37], v[160:163], v[214:217], v[34:37]
	v_mfma_f32_16x16x32_bf16 v[26:29], v[144:147], v[222:225], v[26:29]
	v_mfma_f32_16x16x32_bf16 v[18:21], v[160:163], v[222:225], v[18:21]
	v_mfma_f32_16x16x32_bf16 v[62:65], v[148:151], v[188:191], v[62:65]
	v_mfma_f32_16x16x32_bf16 v[58:61], v[164:167], v[188:191], v[58:61]
	v_mfma_f32_16x16x32_bf16 v[54:57], v[148:151], v[210:213], v[54:57]
	v_mfma_f32_16x16x32_bf16 v[50:53], v[164:167], v[210:213], v[50:53]
	v_mfma_f32_16x16x32_bf16 v[42:45], v[148:151], v[218:221], v[42:45]
	v_mfma_f32_16x16x32_bf16 v[34:37], v[164:167], v[218:221], v[34:37]
	v_mfma_f32_16x16x32_bf16 v[26:29], v[148:151], v[226:229], v[26:29]
	v_mfma_f32_16x16x32_bf16 v[18:21], v[164:167], v[226:229], v[18:21]
	v_mfma_f32_16x16x32_bf16 v[46:49], v[168:171], v[184:187], v[46:49]
	v_mfma_f32_16x16x32_bf16 v[38:41], v[176:179], v[184:187], v[38:41]
	v_mfma_f32_16x16x32_bf16 v[30:33], v[168:171], v[192:195], v[30:33]
	v_mfma_f32_16x16x32_bf16 v[22:25], v[176:179], v[192:195], v[22:25]
	v_mfma_f32_16x16x32_bf16 v[14:17], v[168:171], v[214:217], v[14:17]
	v_mfma_f32_16x16x32_bf16 v[10:13], v[176:179], v[214:217], v[10:13]
	v_mfma_f32_16x16x32_bf16 v[6:9], v[168:171], v[222:225], v[6:9]
	v_mfma_f32_16x16x32_bf16 v[2:5], v[176:179], v[222:225], v[2:5]
	v_mfma_f32_16x16x32_bf16 v[46:49], v[172:175], v[188:191], v[46:49]
	v_mfma_f32_16x16x32_bf16 v[38:41], v[180:183], v[188:191], v[38:41]
	v_mfma_f32_16x16x32_bf16 v[30:33], v[172:175], v[210:213], v[30:33]
	v_mfma_f32_16x16x32_bf16 v[22:25], v[180:183], v[210:213], v[22:25]
	v_mfma_f32_16x16x32_bf16 v[14:17], v[172:175], v[218:221], v[14:17]
	v_mfma_f32_16x16x32_bf16 v[10:13], v[180:183], v[218:221], v[10:13]
	v_mfma_f32_16x16x32_bf16 v[6:9], v[172:175], v[226:229], v[6:9]
	v_mfma_f32_16x16x32_bf16 v[2:5], v[180:183], v[226:229], v[2:5]
	s_barrier
	s_add_i32 s37, s37, 2
	s_add_u32 s3, s3, 0x100
	s_addc_u32 s18, s18, 0
	s_cmp_gt_u32 s37, 19
	s_mov_b64 s[46:47], s[48:49]
	s_cbranch_scc0 .LBB0_411
	s_and_b64 vcc, exec, s[20:21]
	s_cbranch_vccz .LBB0_414
	s_barrier

; #define PG8_WAIT_V(n) asm volatile("s_waitcnt vmcnt(" #n ")" ::: "memory")
; #define PG8_BAR __builtin_amdgcn_s_barrier()
; template <class Epi, class Sched = StaticOrder, bool ALIGN_EPI = true>
; __device__ __forceinline__ void gemm_phase(LAS unsigned char* lds, const Gemm g, const Sched& S, const Epi& E) {
;     ...
;     PG8_WAIT_V(0);
;     if constexpr (!ALIGN_EPI) { if (wr == 0) PG8_BAR; }
;     PG8_BAR;
.LBB0_417:
	s_setprio 0
	s_waitcnt vmcnt(0)
	v_readlane_b32 s16, v254, 43
	v_readlane_b32 s22, v254, 39
	v_readlane_b32 s33, v254, 40
	v_readlane_b32 s17, v254, 44
	v_readlane_b32 s23, v254, 45
	v_readlane_b32 s77, v254, 46
	s_movk_i32 s79, 0x4000
	s_mov_b32 s70, 0x3a000000
	s_barrier

;     __device__ bool next(int i, Unit& u) const { const int idx = i * G + c; if (idx >= 64) return false; u.kp = idx & 3; u.pn = (idx >> 2) & 7; u.pm = 192 + (idx >> 5); return true; }
; #define PG8_STAGE(bufoff, gbase, voff) do { _Pragma("unroll") for (int _i = 0; _i < 2; ++_i) \
;         __builtin_amdgcn_global_load_lds((const unsigned*)((const char*)(gbase) + (voff)[_i]), (LAS unsigned*)(lds + (bufoff) + ldsw + _i * 8192), 16, 0, 0); } while (0)
; #define PG8_WAIT_V(n) asm volatile("s_waitcnt vmcnt(" #n ")" ::: "memory")
; #define PG8_BAR __builtin_amdgcn_s_barrier()
; template <class Epi, class Sched = StaticOrder, bool ALIGN_EPI = true>
; __device__ __forceinline__ void gemm_phase(LAS unsigned char* lds, const Gemm g, const Sched& S, const Epi& E) {
;     ...
;     for (int i = 0; i < 2; ++i) { int R, C; stage_rc(tid * 16 + i * 8192, R, C); const int Rb = Epi::PERM ? ((R & ~31) + perm32(R & 31)) : R;
;         voffA[i] = (unsigned)(R * g.ld + C) * 2u; voffB[i] = (unsigned)(Rb * g.ld + C) * 2u; }
;     const size_t kstep = (size_t)(BK * 2);
;     const size_t hstep = (size_t)HALF * g.ld * 2;
;     const size_t tstep = 2 * hstep;
;     const unsigned ldsw = (unsigned)wid * 1024u;
;     const int aoff = lds_byte(wr * 64 + fr, fq * 8), boff = lds_byte(wc * 32 + fr, fq * 8);
;     ...
;     Unit cur, nxt; int ui = 0;
;     if (!S.next(0, cur)) return;
;     f32x4 acc[2][2][4][2];
; #pragma unroll
;     for (int a = 0; a < 2; ++a)
; #pragma unroll
;         for (int b = 0; b < 2; ++b)
; #pragma unroll
;             for (int m = 0; m < 4; ++m)
; #pragma unroll
;                 for (int n = 0; n < 2; ++n) acc[a][b][m][n] = (f32x4){0.f, 0.f, 0.f, 0.f};
;     bf16x8 At[4][2], B0[2][2], B1[2][2];
;     const char* cA = (const char*)g.A + (size_t)cur.pm * tstep + (size_t)cur.kp * K * 2; const char* cB = (const char*)g.Bt + (size_t)cur.pn * tstep + (size_t)cur.kp * K * 2;
;     PG8_STAGE(PG8_SB(0, 0), cB, voffB); PG8_STAGE(PG8_SB(0, 1), cB + hstep, voffB); PG8_STAGE(PG8_SA(0, 0), cA, voffA); PG8_STAGE(PG8_SA(0, 1), cA + hstep, voffA);
;     if (wr == 1) PG8_BAR;
;     PG8_WAIT_V(2); PG8_BAR;
;     PG8_STAGE(PG8_SB(1, 0), cB + kstep, voffB); PG8_STAGE(PG8_SA(1, 0), cA + kstep, voffA); PG8_STAGE(PG8_SB(1, 1), cB + hstep + kstep, voffB);
;     PG8_WAIT_V(6); PG8_BAR;
.LBB0_461:
	v_lshrrev_b32_e32 v18, 1, v16
	v_and_b32_e32 v18, 24, v18
	s_lshl_b32 s7, s7, 5
	v_and_b32_e32 v17, 15, v16
	v_lshlrev_b32_e32 v19, 1, v18
	v_lshlrev_b32_e32 v16, 2, v16
	s_and_b32 s16, s7, 0x60
	v_lshl_or_b32 v1, s8, 6, v17
	v_lshl_or_b32 v17, v17, 6, v19
	s_lshl_b32 s8, s8, 13
	v_and_b32_e32 v16, 32, v16
	s_lshl_b32 s7, s16, 7
	s_add_i32 m0, s23, 0x18000
	v_lshl_add_u64 v[8:9], v[8:9], 0, s[34:35]
	v_bitop3_b32 v19, v17, s8, v16 bitop3:0xde
	v_bitop3_b32 v144, v17, s7, v16 bitop3:0xde
	s_waitcnt vmcnt(2)
	s_barrier
	global_load_lds_dwordx4 v[8:9], off
	v_lshl_add_u64 v[6:7], v[6:7], 0, s[34:35]
	s_add_i32 m0, s23, 0x1a000
	s_add_i32 s7, s23, 0x8000
	s_add_i32 s8, s23, 0xa000
	global_load_lds_dwordx4 v[6:7], off
	v_lshl_add_u64 v[2:3], v[2:3], 0, s[34:35]
	s_mov_b32 m0, s7
	s_add_u32 s10, s46, 0x80080
	global_load_lds_dwordx4 v[2:3], off
	v_lshl_add_u64 v[2:3], v[4:5], 0, s[34:35]
	s_mov_b32 m0, s8
	s_addc_u32 s11, s47, 0
	global_load_lds_dwordx4 v[2:3], off
	s_add_i32 m0, s23, 0x1c000
	v_lshl_add_u64 v[2:3], s[10:11], 0, v[134:135]
	global_load_lds_dwordx4 v[2:3], off
	v_lshl_add_u64 v[2:3], s[10:11], 0, v[130:131]
	s_add_i32 m0, s23, 0x1e000
	s_cmpk_lt_u32 s9, 0x100
	global_load_lds_dwordx4 v[2:3], off
	v_lshlrev_b32_e32 v2, 15, v14
	v_and_b32_e32 v2, 0xffff0000, v2
	v_lshl_add_u32 v2, v13, 12, v2
	v_and_b32_e32 v3, 1, v14
	v_lshl_or_b32 v2, v3, 6, v2
	v_lshl_add_u32 v138, v15, 1, v2
	v_lshlrev_b32_e32 v2, 15, v10
	v_and_b32_e32 v2, 0xffff0000, v2
	s_waitcnt vmcnt(6)
	v_lshl_add_u32 v2, v11, 12, v2
	v_and_b32_e32 v3, 1, v10
	v_lshl_or_b32 v2, v3, 6, v2
	s_sext_i32_i16 s1, s12
	s_cselect_b64 s[12:13], -1, 0
	v_or_b32_e32 v145, s16, v18
	v_mov_b32_e32 v139, v0
	v_lshl_add_u32 v140, v12, 1, v2
	v_mov_b32_e32 v141, v0
	s_mov_b32 s9, 0
	v_add_u32_e32 v146, 0, v19
	s_barrier
	s_branch .LBB0_464
